# dilated attention: next-tile K/V global loads and their address arithmetic moved from the head of the compute segment to behind the first QK^T MFMA chain (own temporaries v246-v249); on v092
# baseline (speedup 1.0000x reference)
.Lstg_1:
.LBB0_449:
	s_or_b32 s0, s59, 0x41
	s_cmp_le_i32 s0, s56
	s_cselect_b64 s[42:43], -1, 0
	s_cmp_gt_i32 s0, s56
	s_cbranch_scc1 .LBB0_451
	ds_read_b128 v[32:35], v202 offset:13824
	ds_read_b128 v[36:39], v202 offset:13856
	ds_read_b128 v[40:43], v202 offset:13888
	ds_read_b128 v[44:47], v202 offset:13920
	s_waitcnt lgkmcnt(3)
	v_mfma_f32_32x32x16_bf16 v[48:63], v[32:35], v[64:67], 0
	s_waitcnt lgkmcnt(2)
	v_mfma_f32_32x32x16_bf16 v[48:63], v[36:39], v[68:71], v[48:63]
	s_waitcnt lgkmcnt(1)
	v_mfma_f32_32x32x16_bf16 v[48:63], v[40:43], v[72:75], v[48:63]
	s_waitcnt lgkmcnt(0)
	v_mfma_f32_32x32x16_bf16 v[48:63], v[44:47], v[76:79], v[48:63]
.LBB0_451:
	s_cmp_lg_u32 s100, 0
	s_cbranch_scc1 .Lgl_1
	s_add_i32 s0, s59, 0xffffff00
	v_add_u32_e32 v246, s0, v198
	v_ashrrev_i32_e32 v247, 31, v246
	v_lshlrev_b64 v[246:247], 7, v[246:247]
	v_lshl_add_u64 v[248:249], v[166:167], 0, v[246:247]
	v_lshl_add_u64 v[246:247], v[168:169], 0, v[246:247]
	global_load_dwordx4 v[80:83], v[248:249], off
	global_load_dwordx4 v[84:87], v[246:247], off
	v_add_u32_e32 v246, s0, v199
	v_ashrrev_i32_e32 v247, 31, v246
	v_lshlrev_b64 v[246:247], 7, v[246:247]
	v_lshl_add_u64 v[248:249], v[170:171], 0, v[246:247]
	v_lshl_add_u64 v[246:247], v[172:173], 0, v[246:247]
	global_load_dwordx4 v[88:91], v[248:249], off
	global_load_dwordx4 v[92:95], v[246:247], off

.Lstg_0:
.LBB0_486:
	s_sub_i32 s0, s59, 63
	s_cmp_le_i32 s0, s56
	s_cselect_b64 s[42:43], -1, 0
	s_cmp_gt_i32 s0, s56
	s_cbranch_scc1 .LBB0_488
	ds_read_b128 v[32:35], v202 offset:58880
	ds_read_b128 v[36:39], v202 offset:58912
	ds_read_b128 v[40:43], v202 offset:58944
	ds_read_b128 v[44:47], v202 offset:58976
	s_waitcnt lgkmcnt(3)
	v_mfma_f32_32x32x16_bf16 v[48:63], v[32:35], v[64:67], 0
	s_waitcnt lgkmcnt(2)
	v_mfma_f32_32x32x16_bf16 v[48:63], v[36:39], v[68:71], v[48:63]
	s_waitcnt lgkmcnt(1)
	v_mfma_f32_32x32x16_bf16 v[48:63], v[40:43], v[72:75], v[48:63]
	s_waitcnt lgkmcnt(0)
	v_mfma_f32_32x32x16_bf16 v[48:63], v[44:47], v[76:79], v[48:63]
.LBB0_488:
	s_cmp_lg_u32 s100, 0
	s_cbranch_scc1 .Lgl_0
	s_add_i32 s0, s59, 0xfffffe80
	v_add_u32_e32 v246, s0, v198
	v_ashrrev_i32_e32 v247, 31, v246
	v_lshlrev_b64 v[246:247], 7, v[246:247]
	v_lshl_add_u64 v[248:249], v[166:167], 0, v[246:247]
	v_lshl_add_u64 v[246:247], v[168:169], 0, v[246:247]
	global_load_dwordx4 v[96:99], v[248:249], off
	global_load_dwordx4 v[100:103], v[246:247], off
	v_add_u32_e32 v246, s0, v199
	v_ashrrev_i32_e32 v247, 31, v246
	v_lshlrev_b64 v[246:247], 7, v[246:247]
	v_lshl_add_u64 v[248:249], v[170:171], 0, v[246:247]
	v_lshl_add_u64 v[246:247], v[172:173], 0, v[246:247]
	global_load_dwordx4 v[104:107], v[248:249], off
	global_load_dwordx4 v[108:111], v[246:247], off

	.amdhsa_kernel _Z4mega6Paramsii
		.amdhsa_group_segment_fixed_size 0
		.amdhsa_private_segment_fixed_size 0
		.amdhsa_kernarg_size 424
		.amdhsa_user_sgpr_count 2
		.amdhsa_user_sgpr_dispatch_ptr 0
		.amdhsa_user_sgpr_queue_ptr 0
		.amdhsa_user_sgpr_kernarg_segment_ptr 1
		.amdhsa_user_sgpr_dispatch_id 0
		.amdhsa_user_sgpr_kernarg_preload_length 0
		.amdhsa_user_sgpr_kernarg_preload_offset 0
		.amdhsa_user_sgpr_private_segment_size 0
		.amdhsa_uses_dynamic_stack 0
		.amdhsa_enable_private_segment 0
		.amdhsa_system_sgpr_workgroup_id_x 1
		.amdhsa_system_sgpr_workgroup_id_y 0
		.amdhsa_system_sgpr_workgroup_id_z 0
		.amdhsa_system_sgpr_workgroup_info 0
		.amdhsa_system_vgpr_workitem_id 2
		.amdhsa_next_free_vgpr 250
		.amdhsa_next_free_sgpr 101
		.amdhsa_accum_offset 252
		.amdhsa_reserve_vcc 1
		.amdhsa_float_round_mode_32 0
		.amdhsa_float_round_mode_16_64 0
		.amdhsa_float_denorm_mode_32 3
		.amdhsa_float_denorm_mode_16_64 3
		.amdhsa_dx10_clamp 1
		.amdhsa_ieee_mode 1
		.amdhsa_fp16_overflow 0
		.amdhsa_tg_split 0
		.amdhsa_exception_fp_ieee_invalid_op 0
		.amdhsa_exception_fp_denorm_src 0
		.amdhsa_exception_fp_ieee_div_zero 0
		.amdhsa_exception_fp_ieee_overflow 0
		.amdhsa_exception_fp_ieee_underflow 0
		.amdhsa_exception_fp_ieee_inexact 0
		.amdhsa_exception_int_div_zero 0
	.end_amdhsa_kernel

amdhsa.kernels:
  - .agpr_count:     0
    .args:
      - .offset:         0
        .size:           160
        .value_kind:     by_value
      - .offset:         160
        .size:           4
        .value_kind:     by_value
      - .offset:         164
        .size:           4
        .value_kind:     by_value
      - .offset:         168
        .size:           4
        .value_kind:     hidden_block_count_x
      - .offset:         172
        .size:           4
        .value_kind:     hidden_block_count_y
      - .offset:         176
        .size:           4
        .value_kind:     hidden_block_count_z
      - .offset:         180
        .size:           2
        .value_kind:     hidden_group_size_x
      - .offset:         182
        .size:           2
        .value_kind:     hidden_group_size_y
      - .offset:         184
        .size:           2
        .value_kind:     hidden_group_size_z
      - .offset:         186
        .size:           2
        .value_kind:     hidden_remainder_x
      - .offset:         188
        .size:           2
        .value_kind:     hidden_remainder_y
      - .offset:         190
        .size:           2
        .value_kind:     hidden_remainder_z
      - .offset:         208
        .size:           8
        .value_kind:     hidden_global_offset_x
      - .offset:         216
        .size:           8
        .value_kind:     hidden_global_offset_y
      - .offset:         224
        .size:           8
        .value_kind:     hidden_global_offset_z
      - .offset:         232
        .size:           2
        .value_kind:     hidden_grid_dims
      - .offset:         256
        .size:           8
        .value_kind:     hidden_multigrid_sync_arg
      - .offset:         288
        .size:           4
        .value_kind:     hidden_dynamic_lds_size
    .group_segment_fixed_size: 0
    .kernarg_segment_align: 8
    .kernarg_segment_size: 424
    .language:       OpenCL C
    .language_version:
      - 2
      - 0
    .max_flat_workgroup_size: 512
    .name:           _Z4mega6Paramsii
    .private_segment_fixed_size: 0
    .sgpr_count:     107
    .sgpr_spill_count: 3
    .symbol:         _Z4mega6Paramsii.kd
    .uniform_work_group_size: 1
    .uses_dynamic_stack: false
    .vgpr_count:     250
    .vgpr_spill_count: 0
    .wavefront_size: 64
